# E43a: out-L0 EpiNorm epilogue: residual-base loads software-pipelined 6 half-groups ahead into dead operand registers (counted vmcnt) instead of 16 dependent load-wait-use round trips; on E41
# speedup vs baseline: 1.0023x; 1.0023x over previous
.LBB0_713:
	s_or_b64 exec, exec, s[12:13]
	s_lshl_b32 s4, s33, 5
	s_lshl_b32 s5, s6, 8
	s_or_b32 s4, s5, s4
	v_add_u32_e32 v150, s3, v152
	v_and_or_b32 v148, v3, 24, s4
	v_ashrrev_i32_e32 v151, 31, v150
	v_ashrrev_i32_e32 v149, 31, v148
	s_waitcnt lgkmcnt(0)
	v_lshlrev_b64 v[132:133], 10, v[150:151]
	v_readlane_b32 s16, v244, 7
	s_waitcnt vmcnt(0) lgkmcnt(0)
	s_barrier
	v_lshl_add_u64 v[136:137], v[148:149], 2, s[52:53]
	v_lshl_add_u64 v[164:165], v[132:133], 0, v[148:149]
	v_readlane_b32 s17, v244, 8
	global_load_dwordx4 v[140:143], v[136:137], off offset:16
	global_load_dwordx4 v[144:147], v[136:137], off
	v_lshl_add_u64 v[166:167], v[164:165], 2, s[16:17]
	global_load_dwordx4 v[156:159], v[166:167], off nt
	global_load_dwordx4 v[160:163], v[166:167], off offset:16 nt
	v_lshl_add_u32 v3, v152, 2, 0
	ds_read_b32 v168, v3 offset:4096
	v_lshl_add_u64 v[164:165], v[164:165], 1, s[62:63]
	global_load_dwordx4 v[132:135], v[136:137], off offset:528
	s_nop 0
	global_load_dwordx4 v[136:139], v[136:137], off offset:512
	s_lshl_b32 s4, s6, 2
	s_ashr_i32 s5, s4, 31
	s_mov_b32 s11, 0
	v_readlane_b32 s18, v244, 9
	v_readlane_b32 s19, v244, 10
	v_readlane_b32 s20, v244, 11
	v_readlane_b32 s21, v244, 12
	v_readlane_b32 s22, v244, 13
	v_readlane_b32 s23, v244, 14
	v_readlane_b32 s24, v244, 15
	v_readlane_b32 s25, v244, 16
	v_readlane_b32 s26, v244, 17
	v_readlane_b32 s27, v244, 18
	v_readlane_b32 s28, v244, 19
	v_readlane_b32 s29, v244, 20
	v_readlane_b32 s30, v244, 21
	v_readlane_b32 s31, v244, 22
	s_waitcnt vmcnt(0)
	v_mov_b64_e32 v[220:221], v[166:167]
	s_mov_b32 s98, 0x200
	s_mov_b32 s99, 0
	v_lshl_add_u64 v[242:243], v[220:221], 0, s[98:99]
	global_load_dwordx4 v[176:179], v[242:243], off nt
	global_load_dwordx4 v[180:183], v[242:243], off offset:16 nt
	s_mov_b32 s98, 0x10000
	s_mov_b32 s99, 0
	v_lshl_add_u64 v[242:243], v[220:221], 0, s[98:99]
	global_load_dwordx4 v[184:187], v[242:243], off nt
	global_load_dwordx4 v[192:195], v[242:243], off offset:16 nt
	s_mov_b32 s98, 0x10200
	s_mov_b32 s99, 0
	v_lshl_add_u64 v[242:243], v[220:221], 0, s[98:99]
	global_load_dwordx4 v[196:199], v[242:243], off nt
	global_load_dwordx4 v[200:203], v[242:243], off offset:16 nt
	s_mov_b32 s98, 0x20000
	s_mov_b32 s99, 0
	v_lshl_add_u64 v[242:243], v[220:221], 0, s[98:99]
	global_load_dwordx4 v[204:207], v[242:243], off nt
	global_load_dwordx4 v[208:211], v[242:243], off offset:16 nt
	s_mov_b32 s98, 0x20200
	s_mov_b32 s99, 0
	v_lshl_add_u64 v[242:243], v[220:221], 0, s[98:99]
	global_load_dwordx4 v[226:229], v[242:243], off nt
	global_load_dwordx4 v[230:233], v[242:243], off offset:16 nt
	s_mov_b32 s98, 0x30000
	s_mov_b32 s99, 0
	v_lshl_add_u64 v[242:243], v[220:221], 0, s[98:99]
	global_load_dwordx4 v[234:237], v[242:243], off nt
	global_load_dwordx4 v[238:241], v[242:243], off offset:16 nt
	v_pk_mul_f32 v[126:127], v[126:127], v[142:143]
	v_pk_mul_f32 v[130:131], v[130:131], v[146:147]
	v_pk_mul_f32 v[128:129], v[128:129], v[144:145]
	v_pk_mul_f32 v[124:125], v[124:125], v[140:141]
	s_waitcnt lgkmcnt(0)
	v_pk_fma_f32 v[158:159], v[130:131], v[168:169], v[158:159] op_sel_hi:[1,0,1]
	v_pk_fma_f32 v[156:157], v[128:129], v[168:169], v[156:157] op_sel_hi:[1,0,1]
	v_pk_fma_f32 v[162:163], v[126:127], v[168:169], v[162:163] op_sel_hi:[1,0,1]
	v_pk_fma_f32 v[160:161], v[124:125], v[168:169], v[160:161] op_sel_hi:[1,0,1]
	v_cvt_pk_bf16_f32 v124, v156, v157
	v_cvt_pk_bf16_f32 v125, v158, v159
	v_pk_mul_f32 v[122:123], v[122:123], v[138:139]
	v_cvt_pk_bf16_f32 v126, v160, v161
	v_cvt_pk_bf16_f32 v127, v162, v163
	global_store_dwordx4 v[164:165], v[124:127], off sc1
	s_waitcnt vmcnt(11)
	s_nop 1
	v_mov_b64_e32 v[124:125], v[176:177]
	v_mov_b64_e32 v[126:127], v[178:179]
	v_mov_b64_e32 v[128:129], v[180:181]
	v_mov_b64_e32 v[130:131], v[182:183]
	s_mov_b32 s98, 0x30200
	s_mov_b32 s99, 0
	v_lshl_add_u64 v[242:243], v[220:221], 0, s[98:99]
	global_load_dwordx4 v[176:179], v[242:243], off nt
	global_load_dwordx4 v[180:183], v[242:243], off offset:16 nt
	v_pk_mul_f32 v[120:121], v[120:121], v[136:137]
	v_pk_mul_f32 v[118:119], v[118:119], v[134:135]
	v_pk_mul_f32 v[116:117], v[116:117], v[132:133]
	v_mul_f32_e32 v155, v157, v157
	v_mul_f32_e32 v157, v159, v159
	v_mul_f32_e32 v159, v161, v161
	v_mul_f32_e32 v161, v163, v163
	v_fmac_f32_e32 v155, v156, v156
	v_fmac_f32_e32 v157, v158, v158
	v_fmac_f32_e32 v159, v160, v160
	v_fmac_f32_e32 v161, v162, v162
	v_add_f32_e32 v155, v155, v157
	v_add_f32_e32 v156, v159, v161
	v_add_f32_e32 v155, v155, v156
	v_pk_fma_f32 v[122:123], v[122:123], v[168:169], v[126:127] op_sel_hi:[1,0,1]
	v_pk_fma_f32 v[120:121], v[120:121], v[168:169], v[124:125] op_sel_hi:[1,0,1]
	v_pk_fma_f32 v[124:125], v[118:119], v[168:169], v[130:131] op_sel_hi:[1,0,1]
	v_pk_fma_f32 v[126:127], v[116:117], v[168:169], v[128:129] op_sel_hi:[1,0,1]
	v_mul_f32_e32 v116, v121, v121
	v_mul_f32_e32 v117, v123, v123
	v_mul_f32_e32 v118, v127, v127
	v_mul_f32_e32 v119, v125, v125
	v_fmac_f32_e32 v116, v120, v120
	v_fmac_f32_e32 v117, v122, v122
	v_fmac_f32_e32 v118, v126, v126
	v_fmac_f32_e32 v119, v124, v124
	v_add_f32_e32 v116, v116, v117
	v_add_f32_e32 v117, v118, v119
	v_add_f32_e32 v116, v116, v117
	v_add_f32_e32 v116, v155, v116
	ds_bpermute_b32 v117, v153, v116
	v_cvt_pk_bf16_f32 v118, v120, v121
	v_cvt_pk_bf16_f32 v119, v122, v123
	v_cvt_pk_bf16_f32 v120, v126, v127
	v_cvt_pk_bf16_f32 v121, v124, v125
	s_waitcnt lgkmcnt(0)
	v_add_f32_e32 v116, v116, v117
	ds_bpermute_b32 v117, v154, v116
	global_store_dwordx4 v[164:165], v[118:121], off offset:256 sc1
	s_and_saveexec_b64 s[6:7], s[0:1]
	s_cbranch_execz .LBB0_715
	s_waitcnt lgkmcnt(0)
	v_add_f32_e32 v118, v116, v117
	v_lshlrev_b64 v[116:117], 6, v[150:151]
	v_lshl_add_u64 v[116:117], s[86:87], 0, v[116:117]
	v_lshl_add_u64 v[116:117], s[4:5], 2, v[116:117]
	v_lshl_add_u64 v[116:117], v[116:117], 0, s[10:11]
	global_store_dword v[116:117], v118, off
.LBB0_715:
	s_or_b64 exec, exec, s[6:7]
	v_add3_u32 v116, s3, v152, 16
	s_waitcnt lgkmcnt(0)
	v_ashrrev_i32_e32 v117, 31, v116
	v_lshlrev_b64 v[118:119], 10, v[116:117]
	v_readlane_b32 s16, v244, 7
	v_lshl_add_u64 v[126:127], v[118:119], 0, v[148:149]
	v_readlane_b32 s17, v244, 8
	v_pk_mul_f32 v[114:115], v[114:115], v[146:147]
	v_pk_mul_f32 v[112:113], v[112:113], v[144:145]
	v_lshl_add_u64 v[128:129], v[126:127], 2, s[16:17]
	s_waitcnt vmcnt(12)
	s_nop 1
	v_mov_b64_e32 v[118:119], v[184:185]
	v_mov_b64_e32 v[120:121], v[186:187]
	v_mov_b64_e32 v[122:123], v[192:193]
	v_mov_b64_e32 v[124:125], v[194:195]
	s_mov_b32 s98, 0x80000
	s_mov_b32 s99, 0
	v_lshl_add_u64 v[242:243], v[220:221], 0, s[98:99]
	global_load_dwordx4 v[184:187], v[242:243], off nt
	global_load_dwordx4 v[192:195], v[242:243], off offset:16 nt
	ds_read_b32 v130, v3 offset:4160
	v_pk_mul_f32 v[110:111], v[110:111], v[142:143]
	v_pk_mul_f32 v[108:109], v[108:109], v[140:141]
	v_lshl_add_u64 v[126:127], v[126:127], 1, s[62:63]
	v_pk_mul_f32 v[106:107], v[106:107], v[138:139]
	v_pk_mul_f32 v[104:105], v[104:105], v[136:137]
	v_pk_mul_f32 v[102:103], v[102:103], v[134:135]
	v_pk_mul_f32 v[100:101], v[100:101], v[132:133]
	v_readlane_b32 s18, v244, 9
	v_readlane_b32 s19, v244, 10
	v_readlane_b32 s20, v244, 11
	v_readlane_b32 s21, v244, 12
	v_readlane_b32 s22, v244, 13
	v_readlane_b32 s23, v244, 14
	v_readlane_b32 s24, v244, 15
	v_readlane_b32 s25, v244, 16
	v_readlane_b32 s26, v244, 17
	v_readlane_b32 s27, v244, 18
	v_readlane_b32 s28, v244, 19
	v_readlane_b32 s29, v244, 20
	v_readlane_b32 s30, v244, 21
	v_readlane_b32 s31, v244, 22
	s_waitcnt lgkmcnt(0)
	v_pk_fma_f32 v[120:121], v[114:115], v[130:131], v[120:121] op_sel_hi:[1,0,1]
	v_pk_fma_f32 v[118:119], v[112:113], v[130:131], v[118:119] op_sel_hi:[1,0,1]
	v_pk_fma_f32 v[124:125], v[110:111], v[130:131], v[124:125] op_sel_hi:[1,0,1]
	v_pk_fma_f32 v[122:123], v[108:109], v[130:131], v[122:123] op_sel_hi:[1,0,1]
	v_cvt_pk_bf16_f32 v108, v118, v119
	v_cvt_pk_bf16_f32 v109, v120, v121
	v_mul_f32_e32 v119, v119, v119
	v_cvt_pk_bf16_f32 v110, v122, v123
	v_cvt_pk_bf16_f32 v111, v124, v125
	global_store_dwordx4 v[126:127], v[108:111], off sc1
	s_waitcnt vmcnt(13)
	s_nop 1
	v_mov_b64_e32 v[108:109], v[196:197]
	v_mov_b64_e32 v[110:111], v[198:199]
	v_mov_b64_e32 v[112:113], v[200:201]
	v_mov_b64_e32 v[114:115], v[202:203]
	s_mov_b32 s98, 0x80200
	s_mov_b32 s99, 0
	v_lshl_add_u64 v[242:243], v[220:221], 0, s[98:99]
	global_load_dwordx4 v[196:199], v[242:243], off nt
	global_load_dwordx4 v[200:203], v[242:243], off offset:16 nt
	v_mul_f32_e32 v121, v121, v121
	v_mul_f32_e32 v123, v123, v123
	v_mul_f32_e32 v125, v125, v125
	v_fmac_f32_e32 v119, v118, v118
	v_fmac_f32_e32 v121, v120, v120
	v_fmac_f32_e32 v123, v122, v122
	v_fmac_f32_e32 v125, v124, v124
	v_add_f32_e32 v118, v119, v121
	v_add_f32_e32 v119, v123, v125
	v_add_f32_e32 v118, v118, v119
	v_pk_fma_f32 v[106:107], v[106:107], v[130:131], v[110:111] op_sel_hi:[1,0,1]
	v_pk_fma_f32 v[104:105], v[104:105], v[130:131], v[108:109] op_sel_hi:[1,0,1]
	v_pk_fma_f32 v[108:109], v[102:103], v[130:131], v[114:115] op_sel_hi:[1,0,1]
	v_pk_fma_f32 v[110:111], v[100:101], v[130:131], v[112:113] op_sel_hi:[1,0,1]
	v_mul_f32_e32 v100, v105, v105
	v_mul_f32_e32 v101, v107, v107
	v_mul_f32_e32 v102, v111, v111
	v_mul_f32_e32 v103, v109, v109
	v_fmac_f32_e32 v100, v104, v104
	v_fmac_f32_e32 v101, v106, v106
	v_fmac_f32_e32 v102, v110, v110
	v_fmac_f32_e32 v103, v108, v108
	v_add_f32_e32 v100, v100, v101
	v_add_f32_e32 v101, v102, v103
	v_add_f32_e32 v100, v100, v101
	v_add_f32_e32 v100, v118, v100
	ds_bpermute_b32 v101, v153, v100
	v_cvt_pk_bf16_f32 v102, v104, v105
	v_cvt_pk_bf16_f32 v103, v106, v107
	v_cvt_pk_bf16_f32 v104, v110, v111
	v_cvt_pk_bf16_f32 v105, v108, v109
	s_waitcnt lgkmcnt(0)
	v_add_f32_e32 v100, v100, v101
	ds_bpermute_b32 v101, v154, v100
	global_store_dwordx4 v[126:127], v[102:105], off offset:256 sc1
	s_and_saveexec_b64 s[6:7], s[0:1]
	s_cbranch_execz .LBB0_717
	s_waitcnt lgkmcnt(0)
	v_add_f32_e32 v102, v100, v101
	v_lshlrev_b64 v[100:101], 6, v[116:117]
	v_lshl_add_u64 v[100:101], s[86:87], 0, v[100:101]
	v_lshl_add_u64 v[100:101], s[4:5], 2, v[100:101]
	v_lshl_add_u64 v[100:101], v[100:101], 0, s[10:11]
	global_store_dword v[100:101], v102, off
.LBB0_717:
	s_or_b64 exec, exec, s[6:7]
	v_add3_u32 v100, s3, v152, 32
	s_waitcnt lgkmcnt(0)
	v_ashrrev_i32_e32 v101, 31, v100
	v_lshlrev_b64 v[102:103], 10, v[100:101]
	v_readlane_b32 s16, v244, 7
	v_lshl_add_u64 v[110:111], v[102:103], 0, v[148:149]
	v_readlane_b32 s17, v244, 8
	v_pk_mul_f32 v[98:99], v[98:99], v[146:147]
	v_pk_mul_f32 v[96:97], v[96:97], v[144:145]
	v_lshl_add_u64 v[112:113], v[110:111], 2, s[16:17]
	s_waitcnt vmcnt(14)
	s_nop 1
	v_mov_b64_e32 v[102:103], v[204:205]
	v_mov_b64_e32 v[104:105], v[206:207]
	v_mov_b64_e32 v[106:107], v[208:209]
	v_mov_b64_e32 v[108:109], v[210:211]
	s_mov_b32 s98, 0x90000
	s_mov_b32 s99, 0
	v_lshl_add_u64 v[242:243], v[220:221], 0, s[98:99]
	global_load_dwordx4 v[204:207], v[242:243], off nt
	global_load_dwordx4 v[208:211], v[242:243], off offset:16 nt
	ds_read_b32 v114, v3 offset:4224
	v_pk_mul_f32 v[94:95], v[94:95], v[142:143]
	v_pk_mul_f32 v[92:93], v[92:93], v[140:141]
	v_lshl_add_u64 v[110:111], v[110:111], 1, s[62:63]
	v_pk_mul_f32 v[90:91], v[90:91], v[138:139]
	v_pk_mul_f32 v[88:89], v[88:89], v[136:137]
	v_pk_mul_f32 v[86:87], v[86:87], v[134:135]
	v_pk_mul_f32 v[84:85], v[84:85], v[132:133]
	v_readlane_b32 s18, v244, 9
	v_readlane_b32 s19, v244, 10
	v_readlane_b32 s20, v244, 11
	v_readlane_b32 s21, v244, 12
	v_readlane_b32 s22, v244, 13
	v_readlane_b32 s23, v244, 14
	v_readlane_b32 s24, v244, 15
	v_readlane_b32 s25, v244, 16
	v_readlane_b32 s26, v244, 17
	v_readlane_b32 s27, v244, 18
	v_readlane_b32 s28, v244, 19
	v_readlane_b32 s29, v244, 20
	v_readlane_b32 s30, v244, 21
	v_readlane_b32 s31, v244, 22
	s_waitcnt lgkmcnt(0)
	v_pk_fma_f32 v[104:105], v[98:99], v[114:115], v[104:105] op_sel_hi:[1,0,1]
	v_pk_fma_f32 v[102:103], v[96:97], v[114:115], v[102:103] op_sel_hi:[1,0,1]
	v_pk_fma_f32 v[108:109], v[94:95], v[114:115], v[108:109] op_sel_hi:[1,0,1]
	v_pk_fma_f32 v[106:107], v[92:93], v[114:115], v[106:107] op_sel_hi:[1,0,1]
	v_cvt_pk_bf16_f32 v92, v102, v103
	v_cvt_pk_bf16_f32 v93, v104, v105
	v_mul_f32_e32 v103, v103, v103
	v_cvt_pk_bf16_f32 v94, v106, v107
	v_cvt_pk_bf16_f32 v95, v108, v109
	global_store_dwordx4 v[110:111], v[92:95], off sc1
	s_waitcnt vmcnt(15)
	s_nop 1
	v_mov_b64_e32 v[92:93], v[226:227]
	v_mov_b64_e32 v[94:95], v[228:229]
	v_mov_b64_e32 v[96:97], v[230:231]
	v_mov_b64_e32 v[98:99], v[232:233]
	s_mov_b32 s98, 0x90200
	s_mov_b32 s99, 0
	v_lshl_add_u64 v[242:243], v[220:221], 0, s[98:99]
	global_load_dwordx4 v[226:229], v[242:243], off nt
	global_load_dwordx4 v[230:233], v[242:243], off offset:16 nt
	v_mul_f32_e32 v105, v105, v105
	v_mul_f32_e32 v107, v107, v107
	v_mul_f32_e32 v109, v109, v109
	v_fmac_f32_e32 v103, v102, v102
	v_fmac_f32_e32 v105, v104, v104
	v_fmac_f32_e32 v107, v106, v106
	v_fmac_f32_e32 v109, v108, v108
	v_add_f32_e32 v102, v103, v105
	v_add_f32_e32 v103, v107, v109
	v_add_f32_e32 v102, v102, v103
	v_pk_fma_f32 v[90:91], v[90:91], v[114:115], v[94:95] op_sel_hi:[1,0,1]
	v_pk_fma_f32 v[88:89], v[88:89], v[114:115], v[92:93] op_sel_hi:[1,0,1]
	v_pk_fma_f32 v[92:93], v[86:87], v[114:115], v[98:99] op_sel_hi:[1,0,1]
	v_pk_fma_f32 v[94:95], v[84:85], v[114:115], v[96:97] op_sel_hi:[1,0,1]
	v_mul_f32_e32 v84, v89, v89
	v_mul_f32_e32 v85, v91, v91
	v_mul_f32_e32 v86, v95, v95
	v_mul_f32_e32 v87, v93, v93
	v_fmac_f32_e32 v84, v88, v88
	v_fmac_f32_e32 v85, v90, v90
	v_fmac_f32_e32 v86, v94, v94
	v_fmac_f32_e32 v87, v92, v92
	v_add_f32_e32 v84, v84, v85
	v_add_f32_e32 v85, v86, v87
	v_add_f32_e32 v84, v84, v85
	v_add_f32_e32 v84, v102, v84
	ds_bpermute_b32 v85, v153, v84
	v_cvt_pk_bf16_f32 v86, v88, v89
	v_cvt_pk_bf16_f32 v87, v90, v91
	v_cvt_pk_bf16_f32 v88, v94, v95
	v_cvt_pk_bf16_f32 v89, v92, v93
	s_waitcnt lgkmcnt(0)
	v_add_f32_e32 v84, v84, v85
	ds_bpermute_b32 v85, v154, v84
	global_store_dwordx4 v[110:111], v[86:89], off offset:256 sc1
	s_and_saveexec_b64 s[6:7], s[0:1]
	s_cbranch_execz .LBB0_719
	s_waitcnt lgkmcnt(0)
	v_add_f32_e32 v86, v84, v85
	v_lshlrev_b64 v[84:85], 6, v[100:101]
	v_lshl_add_u64 v[84:85], s[86:87], 0, v[84:85]
	v_lshl_add_u64 v[84:85], s[4:5], 2, v[84:85]
	v_lshl_add_u64 v[84:85], v[84:85], 0, s[10:11]
	global_store_dword v[84:85], v86, off
.LBB0_719:
	s_or_b64 exec, exec, s[6:7]
	v_add3_u32 v84, s3, v152, 48
	s_waitcnt lgkmcnt(0)
	v_ashrrev_i32_e32 v85, 31, v84
	v_lshlrev_b64 v[86:87], 10, v[84:85]
	v_readlane_b32 s16, v244, 7
	v_lshl_add_u64 v[94:95], v[86:87], 0, v[148:149]
	v_readlane_b32 s17, v244, 8
	v_pk_mul_f32 v[82:83], v[82:83], v[146:147]
	v_pk_mul_f32 v[80:81], v[80:81], v[144:145]
	v_lshl_add_u64 v[96:97], v[94:95], 2, s[16:17]
	s_waitcnt vmcnt(16)
	s_nop 1
	v_mov_b64_e32 v[86:87], v[234:235]
	v_mov_b64_e32 v[88:89], v[236:237]
	v_mov_b64_e32 v[90:91], v[238:239]
	v_mov_b64_e32 v[92:93], v[240:241]
	s_mov_b32 s98, 0xa0000
	s_mov_b32 s99, 0
	v_lshl_add_u64 v[242:243], v[220:221], 0, s[98:99]
	global_load_dwordx4 v[234:237], v[242:243], off nt
	global_load_dwordx4 v[238:241], v[242:243], off offset:16 nt
	ds_read_b32 v98, v3 offset:4288
	v_pk_mul_f32 v[78:79], v[78:79], v[142:143]
	v_pk_mul_f32 v[76:77], v[76:77], v[140:141]
	v_lshl_add_u64 v[94:95], v[94:95], 1, s[62:63]
	v_pk_mul_f32 v[74:75], v[74:75], v[138:139]
	v_pk_mul_f32 v[72:73], v[72:73], v[136:137]
	v_pk_mul_f32 v[70:71], v[70:71], v[134:135]
	v_pk_mul_f32 v[68:69], v[68:69], v[132:133]
	v_readlane_b32 s18, v244, 9
	v_readlane_b32 s19, v244, 10
	v_readlane_b32 s20, v244, 11
	v_readlane_b32 s21, v244, 12
	v_readlane_b32 s22, v244, 13
	v_readlane_b32 s23, v244, 14
	v_readlane_b32 s24, v244, 15
	v_readlane_b32 s25, v244, 16
	v_readlane_b32 s26, v244, 17
	v_readlane_b32 s27, v244, 18
	v_readlane_b32 s28, v244, 19
	v_readlane_b32 s29, v244, 20
	v_readlane_b32 s30, v244, 21
	v_readlane_b32 s31, v244, 22
	s_waitcnt lgkmcnt(0)
	v_pk_fma_f32 v[88:89], v[82:83], v[98:99], v[88:89] op_sel_hi:[1,0,1]
	v_pk_fma_f32 v[86:87], v[80:81], v[98:99], v[86:87] op_sel_hi:[1,0,1]
	v_pk_fma_f32 v[92:93], v[78:79], v[98:99], v[92:93] op_sel_hi:[1,0,1]
	v_pk_fma_f32 v[90:91], v[76:77], v[98:99], v[90:91] op_sel_hi:[1,0,1]
	v_cvt_pk_bf16_f32 v76, v86, v87
	v_cvt_pk_bf16_f32 v77, v88, v89
	v_mul_f32_e32 v87, v87, v87
	v_cvt_pk_bf16_f32 v78, v90, v91
	v_cvt_pk_bf16_f32 v79, v92, v93
	global_store_dwordx4 v[94:95], v[76:79], off sc1
	s_waitcnt vmcnt(16)
	s_nop 1
	v_mov_b64_e32 v[76:77], v[176:177]
	v_mov_b64_e32 v[78:79], v[178:179]
	v_mov_b64_e32 v[80:81], v[180:181]
	v_mov_b64_e32 v[82:83], v[182:183]
	s_mov_b32 s98, 0xa0200
	s_mov_b32 s99, 0
	v_lshl_add_u64 v[242:243], v[220:221], 0, s[98:99]
	global_load_dwordx4 v[176:179], v[242:243], off nt
	global_load_dwordx4 v[180:183], v[242:243], off offset:16 nt
	v_mul_f32_e32 v89, v89, v89
	v_mul_f32_e32 v91, v91, v91
	v_mul_f32_e32 v93, v93, v93
	v_fmac_f32_e32 v87, v86, v86
	v_fmac_f32_e32 v89, v88, v88
	v_fmac_f32_e32 v91, v90, v90
	v_fmac_f32_e32 v93, v92, v92
	v_add_f32_e32 v86, v87, v89
	v_add_f32_e32 v87, v91, v93
	v_add_f32_e32 v86, v86, v87
	v_pk_fma_f32 v[74:75], v[74:75], v[98:99], v[78:79] op_sel_hi:[1,0,1]
	v_pk_fma_f32 v[72:73], v[72:73], v[98:99], v[76:77] op_sel_hi:[1,0,1]
	v_pk_fma_f32 v[76:77], v[70:71], v[98:99], v[82:83] op_sel_hi:[1,0,1]
	v_pk_fma_f32 v[78:79], v[68:69], v[98:99], v[80:81] op_sel_hi:[1,0,1]
	v_mul_f32_e32 v68, v73, v73
	v_mul_f32_e32 v69, v75, v75
	v_mul_f32_e32 v70, v79, v79
	v_mul_f32_e32 v71, v77, v77
	v_fmac_f32_e32 v68, v72, v72
	v_fmac_f32_e32 v69, v74, v74
	v_fmac_f32_e32 v70, v78, v78
	v_fmac_f32_e32 v71, v76, v76
	v_add_f32_e32 v68, v68, v69
	v_add_f32_e32 v69, v70, v71
	v_add_f32_e32 v68, v68, v69
	v_add_f32_e32 v68, v86, v68
	ds_bpermute_b32 v69, v153, v68
	v_cvt_pk_bf16_f32 v70, v72, v73
	v_cvt_pk_bf16_f32 v71, v74, v75
	v_cvt_pk_bf16_f32 v72, v78, v79
	v_cvt_pk_bf16_f32 v73, v76, v77
	s_waitcnt lgkmcnt(0)
	v_add_f32_e32 v68, v68, v69
	ds_bpermute_b32 v69, v154, v68
	global_store_dwordx4 v[94:95], v[70:73], off offset:256 sc1
	s_and_saveexec_b64 s[6:7], s[0:1]
	s_cbranch_execz .LBB0_721
	s_waitcnt lgkmcnt(0)
	v_add_f32_e32 v70, v68, v69
	v_lshlrev_b64 v[68:69], 6, v[84:85]
	v_lshl_add_u64 v[68:69], s[86:87], 0, v[68:69]
	v_lshl_add_u64 v[68:69], s[4:5], 2, v[68:69]
	v_lshl_add_u64 v[68:69], v[68:69], 0, s[10:11]
	global_store_dword v[68:69], v70, off
.LBB0_721:
	s_or_b64 exec, exec, s[6:7]
	v_add_u32_e32 v68, 0x80, v150
	s_waitcnt lgkmcnt(0)
	v_ashrrev_i32_e32 v69, 31, v68
	v_lshlrev_b64 v[70:71], 10, v[68:69]
	v_readlane_b32 s16, v244, 7
	v_lshl_add_u64 v[78:79], v[70:71], 0, v[148:149]
	v_readlane_b32 s17, v244, 8
	v_pk_mul_f32 v[66:67], v[66:67], v[146:147]
	v_pk_mul_f32 v[64:65], v[64:65], v[144:145]
	v_lshl_add_u64 v[80:81], v[78:79], 2, s[16:17]
	s_waitcnt vmcnt(16)
	s_nop 1
	v_mov_b64_e32 v[70:71], v[184:185]
	v_mov_b64_e32 v[72:73], v[186:187]
	v_mov_b64_e32 v[74:75], v[192:193]
	v_mov_b64_e32 v[76:77], v[194:195]
	s_mov_b32 s98, 0xb0000
	s_mov_b32 s99, 0
	v_lshl_add_u64 v[242:243], v[220:221], 0, s[98:99]
	global_load_dwordx4 v[184:187], v[242:243], off nt
	global_load_dwordx4 v[192:195], v[242:243], off offset:16 nt
	ds_read_b32 v82, v3 offset:4608
	v_pk_mul_f32 v[62:63], v[62:63], v[142:143]
	v_pk_mul_f32 v[60:61], v[60:61], v[140:141]
	v_lshl_add_u64 v[78:79], v[78:79], 1, s[62:63]
	v_pk_mul_f32 v[58:59], v[58:59], v[138:139]
	v_pk_mul_f32 v[56:57], v[56:57], v[136:137]
	v_pk_mul_f32 v[54:55], v[54:55], v[134:135]
	v_pk_mul_f32 v[52:53], v[52:53], v[132:133]
	v_readlane_b32 s18, v244, 9
	v_readlane_b32 s19, v244, 10
	v_readlane_b32 s20, v244, 11
	v_readlane_b32 s21, v244, 12
	v_readlane_b32 s22, v244, 13
	v_readlane_b32 s23, v244, 14
	v_readlane_b32 s24, v244, 15
	v_readlane_b32 s25, v244, 16
	v_readlane_b32 s26, v244, 17
	v_readlane_b32 s27, v244, 18
	v_readlane_b32 s28, v244, 19
	v_readlane_b32 s29, v244, 20
	v_readlane_b32 s30, v244, 21
	v_readlane_b32 s31, v244, 22
	s_waitcnt lgkmcnt(0)
	v_pk_fma_f32 v[72:73], v[66:67], v[82:83], v[72:73] op_sel_hi:[1,0,1]
	v_pk_fma_f32 v[70:71], v[64:65], v[82:83], v[70:71] op_sel_hi:[1,0,1]
	v_pk_fma_f32 v[76:77], v[62:63], v[82:83], v[76:77] op_sel_hi:[1,0,1]
	v_pk_fma_f32 v[74:75], v[60:61], v[82:83], v[74:75] op_sel_hi:[1,0,1]
	v_cvt_pk_bf16_f32 v60, v70, v71
	v_cvt_pk_bf16_f32 v61, v72, v73
	v_mul_f32_e32 v71, v71, v71
	v_cvt_pk_bf16_f32 v62, v74, v75
	v_cvt_pk_bf16_f32 v63, v76, v77
	global_store_dwordx4 v[78:79], v[60:63], off sc1
	s_waitcnt vmcnt(16)
	s_nop 1
	v_mov_b64_e32 v[60:61], v[196:197]
	v_mov_b64_e32 v[62:63], v[198:199]
	v_mov_b64_e32 v[64:65], v[200:201]
	v_mov_b64_e32 v[66:67], v[202:203]
	s_mov_b32 s98, 0xb0200
	s_mov_b32 s99, 0
	v_lshl_add_u64 v[242:243], v[220:221], 0, s[98:99]
	global_load_dwordx4 v[196:199], v[242:243], off nt
	global_load_dwordx4 v[200:203], v[242:243], off offset:16 nt
	v_mul_f32_e32 v73, v73, v73
	v_mul_f32_e32 v75, v75, v75
	v_mul_f32_e32 v77, v77, v77
	v_fmac_f32_e32 v71, v70, v70
	v_fmac_f32_e32 v73, v72, v72
	v_fmac_f32_e32 v75, v74, v74
	v_fmac_f32_e32 v77, v76, v76
	v_add_f32_e32 v70, v71, v73
	v_add_f32_e32 v71, v75, v77
	v_add_f32_e32 v70, v70, v71
	v_pk_fma_f32 v[58:59], v[58:59], v[82:83], v[62:63] op_sel_hi:[1,0,1]
	v_pk_fma_f32 v[56:57], v[56:57], v[82:83], v[60:61] op_sel_hi:[1,0,1]
	v_pk_fma_f32 v[60:61], v[54:55], v[82:83], v[66:67] op_sel_hi:[1,0,1]
	v_pk_fma_f32 v[62:63], v[52:53], v[82:83], v[64:65] op_sel_hi:[1,0,1]
	v_mul_f32_e32 v52, v57, v57
	v_mul_f32_e32 v53, v59, v59
	v_mul_f32_e32 v54, v63, v63
	v_mul_f32_e32 v55, v61, v61
	v_fmac_f32_e32 v52, v56, v56
	v_fmac_f32_e32 v53, v58, v58
	v_fmac_f32_e32 v54, v62, v62
	v_fmac_f32_e32 v55, v60, v60
	v_add_f32_e32 v52, v52, v53
	v_add_f32_e32 v53, v54, v55
	v_add_f32_e32 v52, v52, v53
	v_add_f32_e32 v52, v70, v52
	ds_bpermute_b32 v53, v153, v52
	v_cvt_pk_bf16_f32 v54, v56, v57
	v_cvt_pk_bf16_f32 v55, v58, v59
	v_cvt_pk_bf16_f32 v56, v62, v63
	v_cvt_pk_bf16_f32 v57, v60, v61
	s_waitcnt lgkmcnt(0)
	v_add_f32_e32 v52, v52, v53
	ds_bpermute_b32 v53, v154, v52
	global_store_dwordx4 v[78:79], v[54:57], off offset:256 sc1
	s_and_saveexec_b64 s[6:7], s[0:1]
	s_cbranch_execz .LBB0_723
	s_waitcnt lgkmcnt(0)
	v_add_f32_e32 v54, v52, v53
	v_lshlrev_b64 v[52:53], 6, v[68:69]
	v_lshl_add_u64 v[52:53], s[86:87], 0, v[52:53]
	v_lshl_add_u64 v[52:53], s[4:5], 2, v[52:53]
	v_lshl_add_u64 v[52:53], v[52:53], 0, s[10:11]
	global_store_dword v[52:53], v54, off
.LBB0_723:
	s_or_b64 exec, exec, s[6:7]
	v_add_u32_e32 v52, 0x90, v150
	s_waitcnt lgkmcnt(0)
	v_ashrrev_i32_e32 v53, 31, v52
	v_lshlrev_b64 v[54:55], 10, v[52:53]
	v_readlane_b32 s16, v244, 7
	v_lshl_add_u64 v[62:63], v[54:55], 0, v[148:149]
	v_readlane_b32 s17, v244, 8
	v_pk_mul_f32 v[50:51], v[50:51], v[146:147]
	v_pk_mul_f32 v[48:49], v[48:49], v[144:145]
	v_lshl_add_u64 v[64:65], v[62:63], 2, s[16:17]
	s_waitcnt vmcnt(16)
	s_nop 1
	v_mov_b64_e32 v[54:55], v[204:205]
	v_mov_b64_e32 v[56:57], v[206:207]
	v_mov_b64_e32 v[58:59], v[208:209]
	v_mov_b64_e32 v[60:61], v[210:211]
	ds_read_b32 v66, v3 offset:4672
	v_pk_mul_f32 v[46:47], v[46:47], v[142:143]
	v_pk_mul_f32 v[44:45], v[44:45], v[140:141]
	v_lshl_add_u64 v[62:63], v[62:63], 1, s[62:63]
	v_pk_mul_f32 v[42:43], v[42:43], v[138:139]
	v_pk_mul_f32 v[40:41], v[40:41], v[136:137]
	v_pk_mul_f32 v[38:39], v[38:39], v[134:135]
	v_pk_mul_f32 v[36:37], v[36:37], v[132:133]
	v_readlane_b32 s18, v244, 9
	v_readlane_b32 s19, v244, 10
	v_readlane_b32 s20, v244, 11
	v_readlane_b32 s21, v244, 12
	v_readlane_b32 s22, v244, 13
	v_readlane_b32 s23, v244, 14
	v_readlane_b32 s24, v244, 15
	v_readlane_b32 s25, v244, 16
	v_readlane_b32 s26, v244, 17
	v_readlane_b32 s27, v244, 18
	v_readlane_b32 s28, v244, 19
	v_readlane_b32 s29, v244, 20
	v_readlane_b32 s30, v244, 21
	v_readlane_b32 s31, v244, 22
	s_waitcnt lgkmcnt(0)
	v_pk_fma_f32 v[56:57], v[50:51], v[66:67], v[56:57] op_sel_hi:[1,0,1]
	v_pk_fma_f32 v[54:55], v[48:49], v[66:67], v[54:55] op_sel_hi:[1,0,1]
	v_pk_fma_f32 v[60:61], v[46:47], v[66:67], v[60:61] op_sel_hi:[1,0,1]
	v_pk_fma_f32 v[58:59], v[44:45], v[66:67], v[58:59] op_sel_hi:[1,0,1]
	v_cvt_pk_bf16_f32 v44, v54, v55
	v_cvt_pk_bf16_f32 v45, v56, v57
	v_mul_f32_e32 v55, v55, v55
	v_cvt_pk_bf16_f32 v46, v58, v59
	v_cvt_pk_bf16_f32 v47, v60, v61
	global_store_dwordx4 v[62:63], v[44:47], off sc1
	s_waitcnt vmcnt(14)
	s_nop 1
	v_mov_b64_e32 v[44:45], v[226:227]
	v_mov_b64_e32 v[46:47], v[228:229]
	v_mov_b64_e32 v[48:49], v[230:231]
	v_mov_b64_e32 v[50:51], v[232:233]
	v_mul_f32_e32 v57, v57, v57
	v_mul_f32_e32 v59, v59, v59
	v_mul_f32_e32 v61, v61, v61
	v_fmac_f32_e32 v55, v54, v54
	v_fmac_f32_e32 v57, v56, v56
	v_fmac_f32_e32 v59, v58, v58
	v_fmac_f32_e32 v61, v60, v60
	v_add_f32_e32 v54, v55, v57
	v_add_f32_e32 v55, v59, v61
	v_add_f32_e32 v54, v54, v55
	v_pk_fma_f32 v[42:43], v[42:43], v[66:67], v[46:47] op_sel_hi:[1,0,1]
	v_pk_fma_f32 v[40:41], v[40:41], v[66:67], v[44:45] op_sel_hi:[1,0,1]
	v_pk_fma_f32 v[44:45], v[38:39], v[66:67], v[50:51] op_sel_hi:[1,0,1]
	v_pk_fma_f32 v[46:47], v[36:37], v[66:67], v[48:49] op_sel_hi:[1,0,1]
	v_mul_f32_e32 v36, v41, v41
	v_mul_f32_e32 v37, v43, v43
	v_mul_f32_e32 v38, v47, v47
	v_mul_f32_e32 v39, v45, v45
	v_fmac_f32_e32 v36, v40, v40
	v_fmac_f32_e32 v37, v42, v42
	v_fmac_f32_e32 v38, v46, v46
	v_fmac_f32_e32 v39, v44, v44
	v_add_f32_e32 v36, v36, v37
	v_add_f32_e32 v37, v38, v39
	v_add_f32_e32 v36, v36, v37
	v_add_f32_e32 v36, v54, v36
	ds_bpermute_b32 v37, v153, v36
	v_cvt_pk_bf16_f32 v38, v40, v41
	v_cvt_pk_bf16_f32 v39, v42, v43
	v_cvt_pk_bf16_f32 v40, v46, v47
	v_cvt_pk_bf16_f32 v41, v44, v45
	s_waitcnt lgkmcnt(0)
	v_add_f32_e32 v36, v36, v37
	ds_bpermute_b32 v37, v154, v36
	global_store_dwordx4 v[62:63], v[38:41], off offset:256 sc1
	s_and_saveexec_b64 s[6:7], s[0:1]
	s_cbranch_execz .LBB0_725
	s_waitcnt lgkmcnt(0)
	v_add_f32_e32 v38, v36, v37
	v_lshlrev_b64 v[36:37], 6, v[52:53]
	v_lshl_add_u64 v[36:37], s[86:87], 0, v[36:37]
	v_lshl_add_u64 v[36:37], s[4:5], 2, v[36:37]
	v_lshl_add_u64 v[36:37], v[36:37], 0, s[10:11]
	global_store_dword v[36:37], v38, off
.LBB0_725:
	s_or_b64 exec, exec, s[6:7]
	v_add_u32_e32 v36, 0xa0, v150
	s_waitcnt lgkmcnt(0)
	v_ashrrev_i32_e32 v37, 31, v36
	v_lshlrev_b64 v[38:39], 10, v[36:37]
	v_readlane_b32 s16, v244, 7
	v_lshl_add_u64 v[46:47], v[38:39], 0, v[148:149]
	v_readlane_b32 s17, v244, 8
	v_pk_mul_f32 v[34:35], v[34:35], v[146:147]
	v_pk_mul_f32 v[32:33], v[32:33], v[144:145]
	v_lshl_add_u64 v[48:49], v[46:47], 2, s[16:17]
	s_waitcnt vmcnt(12)
	s_nop 1
	v_mov_b64_e32 v[38:39], v[234:235]
	v_mov_b64_e32 v[40:41], v[236:237]
	v_mov_b64_e32 v[42:43], v[238:239]
	v_mov_b64_e32 v[44:45], v[240:241]
	ds_read_b32 v50, v3 offset:4736
	v_pk_mul_f32 v[30:31], v[30:31], v[142:143]
	v_pk_mul_f32 v[28:29], v[28:29], v[140:141]
	v_lshl_add_u64 v[46:47], v[46:47], 1, s[62:63]
	v_pk_mul_f32 v[26:27], v[26:27], v[138:139]
	v_pk_mul_f32 v[24:25], v[24:25], v[136:137]
	v_pk_mul_f32 v[22:23], v[22:23], v[134:135]
	v_pk_mul_f32 v[20:21], v[20:21], v[132:133]
	v_readlane_b32 s18, v244, 9
	v_readlane_b32 s19, v244, 10
	v_readlane_b32 s20, v244, 11
	v_readlane_b32 s21, v244, 12
	v_readlane_b32 s22, v244, 13
	v_readlane_b32 s23, v244, 14
	v_readlane_b32 s24, v244, 15
	v_readlane_b32 s25, v244, 16
	v_readlane_b32 s26, v244, 17
	v_readlane_b32 s27, v244, 18
	v_readlane_b32 s28, v244, 19
	v_readlane_b32 s29, v244, 20
	v_readlane_b32 s30, v244, 21
	v_readlane_b32 s31, v244, 22
	s_waitcnt lgkmcnt(0)
	v_pk_fma_f32 v[40:41], v[34:35], v[50:51], v[40:41] op_sel_hi:[1,0,1]
	v_pk_fma_f32 v[38:39], v[32:33], v[50:51], v[38:39] op_sel_hi:[1,0,1]
	v_pk_fma_f32 v[44:45], v[30:31], v[50:51], v[44:45] op_sel_hi:[1,0,1]
	v_pk_fma_f32 v[42:43], v[28:29], v[50:51], v[42:43] op_sel_hi:[1,0,1]
	v_cvt_pk_bf16_f32 v28, v38, v39
	v_cvt_pk_bf16_f32 v29, v40, v41
	v_mul_f32_e32 v39, v39, v39
	v_cvt_pk_bf16_f32 v30, v42, v43
	v_cvt_pk_bf16_f32 v31, v44, v45
	global_store_dwordx4 v[46:47], v[28:31], off sc1
	s_waitcnt vmcnt(10)
	s_nop 1
	v_mov_b64_e32 v[28:29], v[176:177]
	v_mov_b64_e32 v[30:31], v[178:179]
	v_mov_b64_e32 v[32:33], v[180:181]
	v_mov_b64_e32 v[34:35], v[182:183]
	v_mul_f32_e32 v41, v41, v41
	v_mul_f32_e32 v43, v43, v43
	v_mul_f32_e32 v45, v45, v45
	v_fmac_f32_e32 v39, v38, v38
	v_fmac_f32_e32 v41, v40, v40
	v_fmac_f32_e32 v43, v42, v42
	v_fmac_f32_e32 v45, v44, v44
	v_add_f32_e32 v38, v39, v41
	v_add_f32_e32 v39, v43, v45
	v_add_f32_e32 v38, v38, v39
	v_pk_fma_f32 v[26:27], v[26:27], v[50:51], v[30:31] op_sel_hi:[1,0,1]
	v_pk_fma_f32 v[24:25], v[24:25], v[50:51], v[28:29] op_sel_hi:[1,0,1]
	v_pk_fma_f32 v[28:29], v[22:23], v[50:51], v[34:35] op_sel_hi:[1,0,1]
	v_pk_fma_f32 v[30:31], v[20:21], v[50:51], v[32:33] op_sel_hi:[1,0,1]
	v_mul_f32_e32 v20, v25, v25
	v_mul_f32_e32 v21, v27, v27
	v_mul_f32_e32 v22, v31, v31
	v_mul_f32_e32 v23, v29, v29
	v_fmac_f32_e32 v20, v24, v24
	v_fmac_f32_e32 v21, v26, v26
	v_fmac_f32_e32 v22, v30, v30
	v_fmac_f32_e32 v23, v28, v28
	v_add_f32_e32 v20, v20, v21
	v_add_f32_e32 v21, v22, v23
	v_add_f32_e32 v20, v20, v21
	v_add_f32_e32 v20, v38, v20
	ds_bpermute_b32 v21, v153, v20
	v_cvt_pk_bf16_f32 v22, v24, v25
	v_cvt_pk_bf16_f32 v23, v26, v27
	v_cvt_pk_bf16_f32 v24, v30, v31
	v_cvt_pk_bf16_f32 v25, v28, v29
	s_waitcnt lgkmcnt(0)
	v_add_f32_e32 v20, v20, v21
	ds_bpermute_b32 v21, v154, v20
	global_store_dwordx4 v[46:47], v[22:25], off offset:256 sc1
	s_and_saveexec_b64 s[6:7], s[0:1]
	s_cbranch_execz .LBB0_727
	s_waitcnt lgkmcnt(0)
	v_add_f32_e32 v22, v20, v21
	v_lshlrev_b64 v[20:21], 6, v[36:37]
	v_lshl_add_u64 v[20:21], s[86:87], 0, v[20:21]
	v_lshl_add_u64 v[20:21], s[4:5], 2, v[20:21]
	v_lshl_add_u64 v[20:21], v[20:21], 0, s[10:11]
	global_store_dword v[20:21], v22, off
.LBB0_727:
	s_or_b64 exec, exec, s[6:7]
	v_add_u32_e32 v20, 0xb0, v150
	s_waitcnt lgkmcnt(0)
	v_ashrrev_i32_e32 v21, 31, v20
	v_lshlrev_b64 v[22:23], 10, v[20:21]
	v_readlane_b32 s16, v244, 7
	v_lshl_add_u64 v[30:31], v[22:23], 0, v[148:149]
	v_readlane_b32 s17, v244, 8
	v_pk_mul_f32 v[18:19], v[18:19], v[146:147]
	v_pk_mul_f32 v[16:17], v[16:17], v[144:145]
	v_lshl_add_u64 v[32:33], v[30:31], 2, s[16:17]
	s_waitcnt vmcnt(8)
	s_nop 1
	v_mov_b64_e32 v[22:23], v[184:185]
	v_mov_b64_e32 v[24:25], v[186:187]
	v_mov_b64_e32 v[26:27], v[192:193]
	v_mov_b64_e32 v[28:29], v[194:195]
	ds_read_b32 v34, v3 offset:4800
	v_pk_mul_f32 v[14:15], v[14:15], v[142:143]
	v_pk_mul_f32 v[12:13], v[12:13], v[140:141]
	v_lshl_add_u64 v[30:31], v[30:31], 1, s[62:63]
	v_pk_mul_f32 v[10:11], v[10:11], v[138:139]
	v_pk_mul_f32 v[8:9], v[8:9], v[136:137]
	v_pk_mul_f32 v[6:7], v[6:7], v[134:135]
	v_pk_mul_f32 v[4:5], v[4:5], v[132:133]
	v_readlane_b32 s18, v244, 9
	v_readlane_b32 s19, v244, 10
	v_readlane_b32 s20, v244, 11
	v_readlane_b32 s21, v244, 12
	v_readlane_b32 s22, v244, 13
	v_readlane_b32 s23, v244, 14
	v_readlane_b32 s24, v244, 15
	v_readlane_b32 s25, v244, 16
	v_readlane_b32 s26, v244, 17
	v_readlane_b32 s27, v244, 18
	v_readlane_b32 s28, v244, 19
	v_readlane_b32 s29, v244, 20
	v_readlane_b32 s30, v244, 21
	v_readlane_b32 s31, v244, 22
	s_waitcnt lgkmcnt(0)
	v_pk_fma_f32 v[24:25], v[18:19], v[34:35], v[24:25] op_sel_hi:[1,0,1]
	v_pk_fma_f32 v[22:23], v[16:17], v[34:35], v[22:23] op_sel_hi:[1,0,1]
	v_pk_fma_f32 v[28:29], v[14:15], v[34:35], v[28:29] op_sel_hi:[1,0,1]
	v_pk_fma_f32 v[26:27], v[12:13], v[34:35], v[26:27] op_sel_hi:[1,0,1]
	v_cvt_pk_bf16_f32 v12, v22, v23
	v_cvt_pk_bf16_f32 v13, v24, v25
	v_mul_f32_e32 v3, v23, v23
	v_cvt_pk_bf16_f32 v14, v26, v27
	v_cvt_pk_bf16_f32 v15, v28, v29
	global_store_dwordx4 v[30:31], v[12:15], off sc1
	s_waitcnt vmcnt(6)
	s_nop 1
	v_mov_b64_e32 v[12:13], v[196:197]
	v_mov_b64_e32 v[14:15], v[198:199]
	v_mov_b64_e32 v[16:17], v[200:201]
	v_mov_b64_e32 v[18:19], v[202:203]
	v_mul_f32_e32 v23, v25, v25
	v_mul_f32_e32 v25, v27, v27
	v_mul_f32_e32 v27, v29, v29
	v_fmac_f32_e32 v3, v22, v22
	v_fmac_f32_e32 v23, v24, v24
	v_fmac_f32_e32 v25, v26, v26
	v_fmac_f32_e32 v27, v28, v28
	v_add_f32_e32 v3, v3, v23
	v_add_f32_e32 v22, v25, v27
	v_add_f32_e32 v3, v3, v22
	v_pk_fma_f32 v[10:11], v[10:11], v[34:35], v[14:15] op_sel_hi:[1,0,1]
	v_pk_fma_f32 v[8:9], v[8:9], v[34:35], v[12:13] op_sel_hi:[1,0,1]
	v_pk_fma_f32 v[12:13], v[6:7], v[34:35], v[18:19] op_sel_hi:[1,0,1]
	v_pk_fma_f32 v[14:15], v[4:5], v[34:35], v[16:17] op_sel_hi:[1,0,1]
	v_mul_f32_e32 v4, v9, v9
	v_mul_f32_e32 v5, v11, v11
	v_mul_f32_e32 v6, v15, v15
	v_mul_f32_e32 v7, v13, v13
	v_fmac_f32_e32 v4, v8, v8
	v_fmac_f32_e32 v5, v10, v10
	v_fmac_f32_e32 v6, v14, v14
	v_fmac_f32_e32 v7, v12, v12
	v_add_f32_e32 v4, v4, v5
	v_add_f32_e32 v5, v6, v7
	v_add_f32_e32 v4, v4, v5
	v_add_f32_e32 v3, v3, v4
	ds_bpermute_b32 v4, v153, v3
	v_cvt_pk_bf16_f32 v6, v8, v9
	v_cvt_pk_bf16_f32 v7, v10, v11
	v_cvt_pk_bf16_f32 v8, v14, v15
	v_cvt_pk_bf16_f32 v9, v12, v13
	s_waitcnt lgkmcnt(0)
	v_add_f32_e32 v3, v3, v4
	ds_bpermute_b32 v4, v154, v3
	global_store_dwordx4 v[30:31], v[6:9], off offset:256 sc1
	s_and_saveexec_b64 s[6:7], s[0:1]
	s_cbranch_execz .LBB0_729
	s_waitcnt lgkmcnt(0)
	v_add_f32_e32 v3, v3, v4
	v_lshlrev_b64 v[4:5], 6, v[20:21]
	v_lshl_add_u64 v[4:5], s[86:87], 0, v[4:5]
	v_lshl_add_u64 v[4:5], s[4:5], 2, v[4:5]
	v_lshl_add_u64 v[4:5], v[4:5], 0, s[10:11]
	global_store_dword v[4:5], v3, off
